# output GEMM epilogue: the 32 serialized residual x loads per unit (load;wait x32) now issue 8 per round with one wait (4 round trips per unit)
# speedup vs baseline: 1.0097x; 1.0068x over previous
;     __device__ __forceinline__ void operator()(const AccT& acc, const Unit& u, int wr, int wc, int fr, int fq) const {
;     ...
;                 f32x4 xv[2][2][2]; float* yr[2]; bool ok[2];
; #pragma unroll
;                 for (int mi = 0; mi < 2; ++mi) {
;                     const int row = row0 + ai * 128 + (2 * mp + mi) * 16;
;                     const float* xr;
;                     if (row < MP) { const int b = row / TP, t = row - b * TP; ok[mi] = t >= NMETA; const size_t o = ((size_t)b * SEQ + (t >= NMETA ? t - NMETA : 0)) * DM + col0; xr = xp + o; yr[mi] = yp + o; }
;                     else { ok[mi] = row < MV; const size_t o = (size_t)(row < MV ? row - MP : 0) * DM + col0; xr = xs + o; yr[mi] = ys + o; }
; #pragma unroll
;                     for (int bj = 0; bj < 2; ++bj)
; #pragma unroll
;                         for (int n = 0; n < 2; ++n) { xv[mi][bj][n] = __builtin_nontemporal_load((const f32x4*)(xr + bj * 128 + n * 4)); asm volatile("" : "+v"(xv[mi][bj][n])); }
;                 }
; #pragma unroll
;                 for (int mi = 0; mi < 2; ++mi)
;                     if (ok[mi]) {
; #pragma unroll
;                         for (int bj = 0; bj < 2; ++bj)
; #pragma unroll
;                             for (int n = 0; n < 2; ++n) __builtin_nontemporal_store(xv[mi][bj][n] + acc[ai][bj][2 * mp + mi][n], (f32x4*)(yr[mi] + bj * 128 + n * 4));
.LBB0_617:
	s_or_b64 exec, exec, s[22:23]
	global_load_dwordx4 v[140:143], v[128:129], off nt
	global_load_dwordx4 v[136:139], v[128:129], off offset:16 nt
	global_load_dwordx4 v[132:135], v[128:129], off offset:512 nt
	v_or_b32_e32 v146, 16, v190
	global_load_dwordx4 v[128:131], v[128:129], off offset:528 nt
	v_cmp_lt_i32_e32 vcc, s82, v146
	s_and_saveexec_b64 s[24:25], vcc
	s_xor_b64 s[24:25], exec, s[24:25]
	s_cmpk_lt_u32 s41, 0x8140
	v_add_u32_e32 v144, 0xffff7fd0, v190
	s_cselect_b64 s[22:23], -1, 0
	v_cndmask_b32_e64 v180, 0, v144, s[22:23]
	v_lshlrev_b64 v[144:145], 10, v[180:181]
	v_lshl_add_u64 v[144:145], v[144:145], 0, v[172:173]
	v_lshlrev_b64 v[146:147], 2, v[144:145]
	v_lshl_add_u64 v[144:145], s[6:7], 0, v[146:147]
	v_lshl_add_u64 v[176:177], s[92:93], 0, v[146:147]
	s_andn2_saveexec_b64 s[24:25], s[24:25]
	s_cbranch_execz .LBB0_621
	v_mul_hi_i32 v144, v146, s96
	v_lshrrev_b32_e32 v145, 31, v144
	v_ashrrev_i32_e32 v144, 12, v144
	v_add_u32_e32 v144, v144, v145
	v_mad_i32_i24 v146, v144, s83, v146
	v_cmp_lt_i32_e32 vcc, 15, v146
	v_ashrrev_i32_e32 v145, 31, v144
	v_max_i32_e32 v146, 16, v146
	v_add_u32_e32 v180, -16, v146
	v_lshlrev_b64 v[144:145], 23, v[144:145]
	v_lshlrev_b64 v[146:147], 10, v[180:181]
	v_lshl_add_u64 v[144:145], v[144:145], 0, v[172:173]
	v_lshl_add_u64 v[144:145], v[144:145], 0, v[146:147]
	v_readlane_b32 s52, v252, 40
	s_andn2_b64 s[50:51], s[20:21], exec
	s_and_b64 s[20:21], s[20:21], exec
	v_lshlrev_b64 v[146:147], 2, v[144:145]
	v_readlane_b32 s66, v252, 54
	v_readlane_b32 s67, v252, 55
	s_or_b64 s[20:21], s[50:51], s[20:21]
	s_andn2_b64 s[22:23], s[22:23], exec
	s_and_b64 s[50:51], vcc, exec
	v_lshl_add_u64 v[144:145], s[4:5], 0, v[146:147]
	v_lshl_add_u64 v[176:177], s[66:67], 0, v[146:147]
	s_or_b64 s[22:23], s[22:23], s[50:51]
	v_readlane_b32 s53, v252, 41
	v_readlane_b32 s54, v252, 42
	v_readlane_b32 s55, v252, 43
	v_readlane_b32 s56, v252, 44
	v_readlane_b32 s57, v252, 45
	v_readlane_b32 s58, v252, 46
	v_readlane_b32 s59, v252, 47
	v_readlane_b32 s60, v252, 48
	v_readlane_b32 s61, v252, 49
	v_readlane_b32 s62, v252, 50
	v_readlane_b32 s63, v252, 51
	v_readlane_b32 s64, v252, 52
	v_readlane_b32 s65, v252, 53
.LBB0_621:
	s_or_b64 exec, exec, s[24:25]
	global_load_dwordx4 v[156:159], v[144:145], off nt
	global_load_dwordx4 v[152:155], v[144:145], off offset:16 nt
	global_load_dwordx4 v[148:151], v[144:145], off offset:512 nt
	global_load_dwordx4 v[144:147], v[144:145], off offset:528 nt
	s_waitcnt vmcnt(0)
	s_and_saveexec_b64 s[24:25], s[20:21]
	s_cbranch_execz .LBB0_623
	v_pk_add_f32 v[126:127], v[126:127], v[142:143]
	v_pk_add_f32 v[124:125], v[124:125], v[140:141]
	v_pk_add_f32 v[122:123], v[122:123], v[138:139]
	v_pk_add_f32 v[120:121], v[120:121], v[136:137]
	v_pk_add_f32 v[118:119], v[118:119], v[134:135]
	v_pk_add_f32 v[116:117], v[116:117], v[132:133]
	v_pk_add_f32 v[110:111], v[110:111], v[130:131]
	v_pk_add_f32 v[108:109], v[108:109], v[128:129]
	global_store_dwordx4 v[174:175], v[124:127], off nt
	global_store_dwordx4 v[174:175], v[120:123], off offset:16 nt
	global_store_dwordx4 v[174:175], v[116:119], off offset:512 nt
	global_store_dwordx4 v[174:175], v[108:111], off offset:528 nt

;     __device__ __forceinline__ void operator()(const AccT& acc, const Unit& u, int wr, int wc, int fr, int fq) const {
;     ...
;                 f32x4 xv[2][2][2]; float* yr[2]; bool ok[2];
; #pragma unroll
;                 for (int mi = 0; mi < 2; ++mi) {
;                     const int row = row0 + ai * 128 + (2 * mp + mi) * 16;
;                     const float* xr;
;                     if (row < MP) { const int b = row / TP, t = row - b * TP; ok[mi] = t >= NMETA; const size_t o = ((size_t)b * SEQ + (t >= NMETA ? t - NMETA : 0)) * DM + col0; xr = xp + o; yr[mi] = yp + o; }
;                     else { ok[mi] = row < MV; const size_t o = (size_t)(row < MV ? row - MP : 0) * DM + col0; xr = xs + o; yr[mi] = ys + o; }
; #pragma unroll
;                     for (int bj = 0; bj < 2; ++bj)
; #pragma unroll
;                         for (int n = 0; n < 2; ++n) { xv[mi][bj][n] = __builtin_nontemporal_load((const f32x4*)(xr + bj * 128 + n * 4)); asm volatile("" : "+v"(xv[mi][bj][n])); }
;                 }
; #pragma unroll
;                 for (int mi = 0; mi < 2; ++mi)
;                     if (ok[mi]) {
; #pragma unroll
;                         for (int bj = 0; bj < 2; ++bj)
; #pragma unroll
;                             for (int n = 0; n < 2; ++n) __builtin_nontemporal_store(xv[mi][bj][n] + acc[ai][bj][2 * mp + mi][n], (f32x4*)(yr[mi] + bj * 128 + n * 4));
.LBB0_629:
	s_or_b64 exec, exec, s[22:23]
	global_load_dwordx4 v[108:111], v[96:97], off nt
	global_load_dwordx4 v[104:107], v[96:97], off offset:16 nt
	global_load_dwordx4 v[100:103], v[96:97], off offset:512 nt
	v_or_b32_e32 v114, 48, v190
	global_load_dwordx4 v[96:99], v[96:97], off offset:528 nt
	v_cmp_lt_i32_e32 vcc, s82, v114
	s_and_saveexec_b64 s[24:25], vcc
	s_xor_b64 s[24:25], exec, s[24:25]
	s_cmpk_lt_u32 s41, 0x8140
	v_add_u32_e32 v112, 0xffff7ff0, v190
	s_cselect_b64 s[22:23], -1, 0
	v_cndmask_b32_e64 v180, 0, v112, s[22:23]
	v_lshlrev_b64 v[112:113], 10, v[180:181]
	v_lshl_add_u64 v[112:113], v[112:113], 0, v[172:173]
	v_lshlrev_b64 v[114:115], 2, v[112:113]
	v_lshl_add_u64 v[112:113], s[6:7], 0, v[114:115]
	v_lshl_add_u64 v[130:131], s[92:93], 0, v[114:115]
	s_andn2_saveexec_b64 s[24:25], s[24:25]
	s_cbranch_execz .LBB0_633
	v_mul_hi_i32 v112, v114, s96
	v_lshrrev_b32_e32 v113, 31, v112
	v_ashrrev_i32_e32 v112, 12, v112
	v_add_u32_e32 v112, v112, v113
	v_mad_i32_i24 v114, v112, s83, v114
	v_cmp_lt_i32_e32 vcc, 15, v114
	v_ashrrev_i32_e32 v113, 31, v112
	v_max_i32_e32 v114, 16, v114
	v_add_u32_e32 v180, -16, v114
	v_lshlrev_b64 v[112:113], 23, v[112:113]
	v_lshlrev_b64 v[114:115], 10, v[180:181]
	v_lshl_add_u64 v[112:113], v[112:113], 0, v[172:173]
	v_lshl_add_u64 v[112:113], v[112:113], 0, v[114:115]
	v_readlane_b32 s52, v252, 40
	s_andn2_b64 s[50:51], s[20:21], exec
	s_and_b64 s[20:21], s[20:21], exec
	v_lshlrev_b64 v[114:115], 2, v[112:113]
	v_readlane_b32 s66, v252, 54
	v_readlane_b32 s67, v252, 55
	s_or_b64 s[20:21], s[50:51], s[20:21]
	s_andn2_b64 s[22:23], s[22:23], exec
	s_and_b64 s[50:51], vcc, exec
	v_lshl_add_u64 v[112:113], s[4:5], 0, v[114:115]
	v_lshl_add_u64 v[130:131], s[66:67], 0, v[114:115]
	s_or_b64 s[22:23], s[22:23], s[50:51]
	v_readlane_b32 s53, v252, 41
	v_readlane_b32 s54, v252, 42
	v_readlane_b32 s55, v252, 43
	v_readlane_b32 s56, v252, 44
	v_readlane_b32 s57, v252, 45
	v_readlane_b32 s58, v252, 46
	v_readlane_b32 s59, v252, 47
	v_readlane_b32 s60, v252, 48
	v_readlane_b32 s61, v252, 49
	v_readlane_b32 s62, v252, 50
	v_readlane_b32 s63, v252, 51
	v_readlane_b32 s64, v252, 52
	v_readlane_b32 s65, v252, 53
.LBB0_633:
	s_or_b64 exec, exec, s[24:25]
	global_load_dwordx4 v[124:127], v[112:113], off nt
	global_load_dwordx4 v[120:123], v[112:113], off offset:16 nt
	global_load_dwordx4 v[116:119], v[112:113], off offset:512 nt
	global_load_dwordx4 v[112:115], v[112:113], off offset:528 nt
	s_waitcnt vmcnt(0)
	s_and_saveexec_b64 s[24:25], s[20:21]
	s_cbranch_execz .LBB0_635
	v_pk_add_f32 v[94:95], v[94:95], v[110:111]
	v_pk_add_f32 v[92:93], v[92:93], v[108:109]
	v_pk_add_f32 v[90:91], v[90:91], v[106:107]
	v_pk_add_f32 v[88:89], v[88:89], v[104:105]
	v_pk_add_f32 v[86:87], v[86:87], v[102:103]
	v_pk_add_f32 v[84:85], v[84:85], v[100:101]
	v_pk_add_f32 v[78:79], v[78:79], v[98:99]
	v_pk_add_f32 v[76:77], v[76:77], v[96:97]
	global_store_dwordx4 v[128:129], v[92:95], off nt
	global_store_dwordx4 v[128:129], v[88:91], off offset:16 nt
	global_store_dwordx4 v[128:129], v[84:87], off offset:512 nt
	global_store_dwordx4 v[128:129], v[76:79], off offset:528 nt

;     __device__ __forceinline__ void operator()(const AccT& acc, const Unit& u, int wr, int wc, int fr, int fq) const {
;     ...
;                 f32x4 xv[2][2][2]; float* yr[2]; bool ok[2];
; #pragma unroll
;                 for (int mi = 0; mi < 2; ++mi) {
;                     const int row = row0 + ai * 128 + (2 * mp + mi) * 16;
;                     const float* xr;
;                     if (row < MP) { const int b = row / TP, t = row - b * TP; ok[mi] = t >= NMETA; const size_t o = ((size_t)b * SEQ + (t >= NMETA ? t - NMETA : 0)) * DM + col0; xr = xp + o; yr[mi] = yp + o; }
;                     else { ok[mi] = row < MV; const size_t o = (size_t)(row < MV ? row - MP : 0) * DM + col0; xr = xs + o; yr[mi] = ys + o; }
; #pragma unroll
;                     for (int bj = 0; bj < 2; ++bj)
; #pragma unroll
;                         for (int n = 0; n < 2; ++n) { xv[mi][bj][n] = __builtin_nontemporal_load((const f32x4*)(xr + bj * 128 + n * 4)); asm volatile("" : "+v"(xv[mi][bj][n])); }
;                 }
; #pragma unroll
;                 for (int mi = 0; mi < 2; ++mi)
;                     if (ok[mi]) {
; #pragma unroll
;                         for (int bj = 0; bj < 2; ++bj)
; #pragma unroll
;                             for (int n = 0; n < 2; ++n) __builtin_nontemporal_store(xv[mi][bj][n] + acc[ai][bj][2 * mp + mi][n], (f32x4*)(yr[mi] + bj * 128 + n * 4));
.LBB0_641:
	s_or_b64 exec, exec, s[22:23]
	global_load_dwordx4 v[76:79], v[64:65], off nt
	global_load_dwordx4 v[72:75], v[64:65], off offset:16 nt
	global_load_dwordx4 v[68:71], v[64:65], off offset:512 nt
	s_movk_i32 s2, 0x7faf
	global_load_dwordx4 v[64:67], v[64:65], off offset:528 nt
	v_add_u32_e32 v82, 0x90, v190
	v_cmp_lt_i32_e32 vcc, s2, v190
	s_and_saveexec_b64 s[24:25], vcc
	s_xor_b64 s[24:25], exec, s[24:25]
	s_mov_b32 s2, 0x8140
	v_add_u32_e32 v80, 0xffff8050, v190
	v_cmp_gt_u32_e64 s[22:23], s2, v82
	s_nop 1
	v_cndmask_b32_e64 v180, 0, v80, s[22:23]
	v_lshlrev_b64 v[80:81], 10, v[180:181]
	v_lshl_add_u64 v[80:81], v[80:81], 0, v[172:173]
	v_lshlrev_b64 v[82:83], 2, v[80:81]
	v_lshl_add_u64 v[80:81], s[6:7], 0, v[82:83]
	v_lshl_add_u64 v[98:99], s[92:93], 0, v[82:83]
	s_andn2_saveexec_b64 s[24:25], s[24:25]
	s_cbranch_execz .LBB0_645
	v_mul_hi_i32 v80, v82, s96
	v_lshrrev_b32_e32 v81, 31, v80
	v_ashrrev_i32_e32 v80, 12, v80
	v_add_u32_e32 v80, v80, v81
	v_mad_i32_i24 v82, v80, s83, v82
	v_cmp_lt_i32_e32 vcc, 15, v82
	v_ashrrev_i32_e32 v81, 31, v80
	v_max_i32_e32 v82, 16, v82
	v_add_u32_e32 v180, -16, v82
	v_lshlrev_b64 v[80:81], 23, v[80:81]
	v_lshlrev_b64 v[82:83], 10, v[180:181]
	v_lshl_add_u64 v[80:81], v[80:81], 0, v[172:173]
	v_lshl_add_u64 v[80:81], v[80:81], 0, v[82:83]
	v_readlane_b32 s52, v252, 40
	s_andn2_b64 s[50:51], s[20:21], exec
	s_and_b64 s[20:21], s[20:21], exec
	v_lshlrev_b64 v[82:83], 2, v[80:81]
	v_readlane_b32 s66, v252, 54
	v_readlane_b32 s67, v252, 55
	s_or_b64 s[20:21], s[50:51], s[20:21]
	s_andn2_b64 s[22:23], s[22:23], exec
	s_and_b64 s[50:51], vcc, exec
	v_lshl_add_u64 v[80:81], s[4:5], 0, v[82:83]
	v_lshl_add_u64 v[98:99], s[66:67], 0, v[82:83]
	s_or_b64 s[22:23], s[22:23], s[50:51]
	v_readlane_b32 s53, v252, 41
	v_readlane_b32 s54, v252, 42
	v_readlane_b32 s55, v252, 43
	v_readlane_b32 s56, v252, 44
	v_readlane_b32 s57, v252, 45
	v_readlane_b32 s58, v252, 46
	v_readlane_b32 s59, v252, 47
	v_readlane_b32 s60, v252, 48
	v_readlane_b32 s61, v252, 49
	v_readlane_b32 s62, v252, 50
	v_readlane_b32 s63, v252, 51
	v_readlane_b32 s64, v252, 52
	v_readlane_b32 s65, v252, 53
.LBB0_645:
	s_or_b64 exec, exec, s[24:25]
	global_load_dwordx4 v[92:95], v[80:81], off nt
	global_load_dwordx4 v[88:91], v[80:81], off offset:16 nt
	global_load_dwordx4 v[84:87], v[80:81], off offset:512 nt
	global_load_dwordx4 v[80:83], v[80:81], off offset:528 nt
	s_waitcnt vmcnt(0)
	s_and_saveexec_b64 s[24:25], s[20:21]
	s_cbranch_execz .LBB0_647
	v_pk_add_f32 v[62:63], v[62:63], v[78:79]
	v_pk_add_f32 v[60:61], v[60:61], v[76:77]
	v_pk_add_f32 v[58:59], v[58:59], v[74:75]
	v_pk_add_f32 v[56:57], v[56:57], v[72:73]
	v_pk_add_f32 v[54:55], v[54:55], v[70:71]
	v_pk_add_f32 v[52:53], v[52:53], v[68:69]
	v_pk_add_f32 v[46:47], v[46:47], v[66:67]
	v_pk_add_f32 v[44:45], v[44:45], v[64:65]
	global_store_dwordx4 v[96:97], v[60:63], off nt
	global_store_dwordx4 v[96:97], v[56:59], off offset:16 nt
	global_store_dwordx4 v[96:97], v[52:55], off offset:512 nt
	global_store_dwordx4 v[96:97], v[44:47], off offset:528 nt

;     __device__ __forceinline__ void operator()(const AccT& acc, const Unit& u, int wr, int wc, int fr, int fq) const {
;     ...
;                 f32x4 xv[2][2][2]; float* yr[2]; bool ok[2];
; #pragma unroll
;                 for (int mi = 0; mi < 2; ++mi) {
;                     const int row = row0 + ai * 128 + (2 * mp + mi) * 16;
;                     const float* xr;
;                     if (row < MP) { const int b = row / TP, t = row - b * TP; ok[mi] = t >= NMETA; const size_t o = ((size_t)b * SEQ + (t >= NMETA ? t - NMETA : 0)) * DM + col0; xr = xp + o; yr[mi] = yp + o; }
;                     else { ok[mi] = row < MV; const size_t o = (size_t)(row < MV ? row - MP : 0) * DM + col0; xr = xs + o; yr[mi] = ys + o; }
; #pragma unroll
;                     for (int bj = 0; bj < 2; ++bj)
; #pragma unroll
;                         for (int n = 0; n < 2; ++n) { xv[mi][bj][n] = __builtin_nontemporal_load((const f32x4*)(xr + bj * 128 + n * 4)); asm volatile("" : "+v"(xv[mi][bj][n])); }
;                 }
; #pragma unroll
;                 for (int mi = 0; mi < 2; ++mi)
;                     if (ok[mi]) {
; #pragma unroll
;                         for (int bj = 0; bj < 2; ++bj)
; #pragma unroll
;                             for (int n = 0; n < 2; ++n) __builtin_nontemporal_store(xv[mi][bj][n] + acc[ai][bj][2 * mp + mi][n], (f32x4*)(yr[mi] + bj * 128 + n * 4));
.LBB0_653:
	s_or_b64 exec, exec, s[22:23]
	global_load_dwordx4 v[44:47], v[32:33], off nt
	global_load_dwordx4 v[40:43], v[32:33], off offset:16 nt
	global_load_dwordx4 v[36:39], v[32:33], off offset:512 nt
	s_movk_i32 s2, 0x7f8f
	global_load_dwordx4 v[32:35], v[32:33], off offset:528 nt
	v_add_u32_e32 v50, 0xb0, v190
	v_cmp_lt_i32_e32 vcc, s2, v190
	s_and_saveexec_b64 s[24:25], vcc
	s_xor_b64 s[24:25], exec, s[24:25]
	s_mov_b32 s2, 0x8140
	v_add_u32_e32 v48, 0xffff8070, v190
	v_cmp_gt_u32_e64 s[22:23], s2, v50
	s_nop 1
	v_cndmask_b32_e64 v180, 0, v48, s[22:23]
	v_lshlrev_b64 v[48:49], 10, v[180:181]
	v_lshl_add_u64 v[48:49], v[48:49], 0, v[172:173]
	v_lshlrev_b64 v[50:51], 2, v[48:49]
	v_lshl_add_u64 v[48:49], s[6:7], 0, v[50:51]
	v_lshl_add_u64 v[66:67], s[92:93], 0, v[50:51]
	s_andn2_saveexec_b64 s[24:25], s[24:25]
	s_cbranch_execz .LBB0_657
	v_mul_hi_i32 v48, v50, s96
	v_lshrrev_b32_e32 v49, 31, v48
	v_ashrrev_i32_e32 v48, 12, v48
	v_add_u32_e32 v48, v48, v49
	v_mad_i32_i24 v50, v48, s83, v50
	v_cmp_lt_i32_e32 vcc, 15, v50
	v_ashrrev_i32_e32 v49, 31, v48
	v_max_i32_e32 v50, 16, v50
	v_add_u32_e32 v180, -16, v50
	v_lshlrev_b64 v[48:49], 23, v[48:49]
	v_lshlrev_b64 v[50:51], 10, v[180:181]
	v_lshl_add_u64 v[48:49], v[48:49], 0, v[172:173]
	v_lshl_add_u64 v[48:49], v[48:49], 0, v[50:51]
	v_readlane_b32 s52, v252, 40
	s_andn2_b64 s[50:51], s[20:21], exec
	s_and_b64 s[20:21], s[20:21], exec
	v_lshlrev_b64 v[50:51], 2, v[48:49]
	v_readlane_b32 s66, v252, 54
	v_readlane_b32 s67, v252, 55
	s_or_b64 s[20:21], s[50:51], s[20:21]
	s_andn2_b64 s[22:23], s[22:23], exec
	s_and_b64 s[50:51], vcc, exec
	v_lshl_add_u64 v[48:49], s[4:5], 0, v[50:51]
	v_lshl_add_u64 v[66:67], s[66:67], 0, v[50:51]
	s_or_b64 s[22:23], s[22:23], s[50:51]
	v_readlane_b32 s53, v252, 41
	v_readlane_b32 s54, v252, 42
	v_readlane_b32 s55, v252, 43
	v_readlane_b32 s56, v252, 44
	v_readlane_b32 s57, v252, 45
	v_readlane_b32 s58, v252, 46
	v_readlane_b32 s59, v252, 47
	v_readlane_b32 s60, v252, 48
	v_readlane_b32 s61, v252, 49
	v_readlane_b32 s62, v252, 50
	v_readlane_b32 s63, v252, 51
	v_readlane_b32 s64, v252, 52
	v_readlane_b32 s65, v252, 53
.LBB0_657:
	s_or_b64 exec, exec, s[24:25]
	global_load_dwordx4 v[60:63], v[48:49], off nt
	global_load_dwordx4 v[56:59], v[48:49], off offset:16 nt
	global_load_dwordx4 v[52:55], v[48:49], off offset:512 nt
	global_load_dwordx4 v[48:51], v[48:49], off offset:528 nt
	s_waitcnt vmcnt(0)
	s_and_saveexec_b64 s[24:25], s[20:21]
	s_cbranch_execz .LBB0_659
	v_pk_add_f32 v[10:11], v[10:11], v[42:43]
	v_pk_add_f32 v[8:9], v[8:9], v[40:41]
	global_store_dwordx4 v[64:65], v[8:11], off offset:16 nt
	v_pk_add_f32 v[14:15], v[14:15], v[46:47]
	v_pk_add_f32 v[12:13], v[12:13], v[44:45]
	v_pk_add_f32 v[10:11], v[30:31], v[38:39]
	v_pk_add_f32 v[8:9], v[28:29], v[36:37]
	global_store_dwordx4 v[64:65], v[8:11], off offset:512 nt
	global_store_dwordx4 v[64:65], v[12:15], off nt
	s_nop 0
	v_pk_add_f32 v[10:11], v[26:27], v[34:35]
	v_pk_add_f32 v[8:9], v[24:25], v[32:33]
	global_store_dwordx4 v[64:65], v[8:11], off offset:528 nt
